# lru3: the 16 loads of an item issued up front with counted waits; attention item prologue keeps the Q fragment loads in flight across the barrier
# speedup vs baseline: 1.0061x; 1.0061x over previous
; DI int kswz(int key) { return (((key >> 3) & 3) << 2) | (key & 3); }
; DI void attn_item(const Params& p, int l, bool isS, int b, int h, int cp, char* smem) {
;     ...
;   const int kkey = tid >> 4, vvd = tid >> 3;
;   const int kgch = (tid & 15) ^ kswz(kkey);
;   const int vgch = (tid & 7) ^ ((vvd >> 1) & 7);
;   const int soff = tid * 16;
;   auto issue_k = [&](int kt) {
; #pragma unroll
;     for (int i = 0; i < 2; ++i)
;       __builtin_amdgcn_global_load_lds((const unsigned*)(Kg + (size_t)(kt * 64 + kkey + i * 32) * 512 + kgch * 8), (unsigned*)(Ks + (kt & 1) * 16384 + soff + i * 8192), 16, 0, 0);
;   };
;   auto issue_v = [&](int kt) {
; #pragma unroll
;     for (int i = 0; i < 2; ++i)
;       __builtin_amdgcn_global_load_lds((const unsigned*)(Vg + (size_t)(vvd + i * 64) * vstride + kt * 64 + vgch * 8), (unsigned*)(Vs + (kt & 1) * 16384 + soff + i * 8192), 16, 0, 0);
;   };
;     ...
;   asm volatile("s_waitcnt vmcnt(0) lgkmcnt(0)" ::: "memory");
;   __builtin_amdgcn_s_barrier();
;   issue_k(0); issue_v(0);
;   if (nkt > 1) issue_k(1);
.LBB0_1358:
	s_or_b64 exec, exec, s[36:37]
	s_add_u32 s28, s28, s8
	v_ashrrev_i32_e32 v136, 4, v54
	s_addc_u32 s29, s29, 0
	v_lshrrev_b32_e32 v0, 1, v136
	s_add_u32 s9, s94, s34
	v_ashrrev_i32_e32 v2, 3, v54
	v_and_b32_e32 v0, 12, v0
	v_and_b32_e32 v1, 3, v136
	s_addc_u32 s20, s95, s35
	s_mul_hi_u32 s35, s11, s30
	s_mul_i32 s34, s11, s30
	v_bitop3_b32 v24, v0, v55, v1 bitop3:0x36
	v_lshrrev_b32_e32 v0, 1, v2
	v_ashrrev_i32_e32 v137, 31, v136
	s_lshl_b64 s[34:35], s[34:35], 8
	v_xor_b32_e32 v22, v0, v54
	v_lshlrev_b64 v[0:1], 10, v[136:137]
	v_lshl_add_u32 v133, v54, 4, 16
	s_add_u32 s34, s9, s34
	v_lshl_add_u64 v[0:1], s[28:29], 0, v[0:1]
	v_lshlrev_b32_e32 v20, 4, v24
	v_mov_b32_e32 v21, v173
	v_readfirstlane_b32 s9, v133
	v_add_u32_e32 v23, 0x2000, v133
	v_lshl_add_u64 v[20:21], v[0:1], 0, v[20:21]
	s_mov_b32 m0, s9
	s_mov_b64 s[24:25], 0x8000
	v_readfirstlane_b32 s9, v23
	s_waitcnt lgkmcnt(0)
	s_barrier
	global_load_lds_dwordx4 v[20:21], off
	v_lshl_add_u64 v[20:21], v[20:21], 0, s[24:25]
	s_mov_b32 m0, s9
	s_addc_u32 s35, s20, s35
	global_load_lds_dwordx4 v[20:21], off
	v_mad_i64_i32 v[20:21], s[36:37], s30, v2, 0
	v_lshlrev_b32_e32 v22, 4, v22
	v_lshl_add_u64 v[20:21], v[20:21], 1, s[34:35]
	v_and_b32_e32 v22, 0x70, v22
	v_mov_b32_e32 v23, v173
	v_lshl_add_u64 v[138:139], v[20:21], 0, v[22:23]
	v_add_u32_e32 v20, 0x8000, v133
	v_add_u32_e32 v2, 64, v2
	v_readfirstlane_b32 s9, v20
	v_mad_i64_i32 v[20:21], s[30:31], s30, v2, 0
	v_add_u32_e32 v2, 0xa000, v133
	s_mov_b32 m0, s9
	v_lshl_add_u64 v[20:21], v[20:21], 1, s[34:35]
	v_readfirstlane_b32 s9, v2
	global_load_lds_dwordx4 v[138:139], off
	v_lshl_add_u64 v[140:141], v[20:21], 0, v[22:23]
	s_mov_b32 m0, s9
	s_lshl_b32 s11, s10, 1
	global_load_lds_dwordx4 v[140:141], off
	s_add_i32 s20, s11, 2
	s_and_b64 s[30:31], s[26:27], exec
	s_cselect_b32 s9, 33, s20
	v_lshlrev_b32_e32 v2, 3, v24
	s_cmp_lt_i32 s9, 2
	v_lshlrev_b32_e32 v52, 1, v2
	s_cbranch_scc1 .LBB0_1360
	v_mov_b32_e32 v53, v173
	v_add_u32_e32 v2, 0x4000, v133
	v_lshl_add_u64 v[0:1], v[0:1], 0, v[52:53]
	s_mov_b64 s[24:25], 0x10000
	v_readfirstlane_b32 s10, v2
	v_add_u32_e32 v2, 0x6000, v133
	v_lshl_add_u64 v[20:21], v[0:1], 0, s[24:25]
	s_mov_b32 m0, s10
	s_mov_b64 s[30:31], 0x18000
	v_readfirstlane_b32 s10, v2
	global_load_lds_dwordx4 v[20:21], off
	v_lshl_add_u64 v[0:1], v[0:1], 0, s[30:31]
	s_mov_b32 m0, s10
	s_nop 0
	global_load_lds_dwordx4 v[0:1], off

; DI int TID() { int t = threadIdx.x & 255; asm volatile("" : "+v"(t)); return t; }
; DI float bf2f(u16 h) { return __uint_as_float(((unsigned)h) << 16); }
; DI unsigned pack2(float a, float b) { f32v2_t v = {a, b}; bf16v2_t r = __builtin_convertvector(v, bf16v2_t); return __builtin_bit_cast(unsigned, r); }
; DI float gelu_tanh(float x) { float u = 0.7978845608028654f * (x + 0.044715f * x * x * x); return x * sigmoidf_(2.f * u); }
; #define HS() (smem + (TID512() >> 8) * HALF_LDS)
; DI void lru3_item(const Params& p, int it) {
;   const u16* HL = (const u16*)(p.ws + O_HL);
;   const u16* PPp = (const u16*)(p.ws + O_PP);
;   const u16* LG = (const u16*)(p.ws + O_LG);
;   const float* HS = (const float*)(p.ws + O_HS);
;   u16* OL = (u16*)(p.ws + O_OL);
; #pragma unroll
;   for (int i = 0; i < 4; ++i) {
;     const int id = TID() + i * 256;
;     const int row = it * 8 + (id >> 7), c4 = (id & 127) * 4;
;     const int ci = row < MP ? (row >> 6) : MP / 64 + ((row - MP) >> 5);
;     const size_t o = (size_t)row * 512 + c4;
;     const uint2 hl = *(const uint2*)(HL + o), pp = *(const uint2*)(PPp + o), lg = *(const uint2*)(LG + o);
;     const float4 hs = *(const float4*)(HS + (size_t)ci * 512 + c4);
;     float y0 = (bf2f(hl.x & 0xffff) + bf2f(pp.x & 0xffff) * hs.x) * gelu_tanh(bf2f(lg.x & 0xffff));
;     float y1 = (bf2f(hl.x >> 16) + bf2f(pp.x >> 16) * hs.y) * gelu_tanh(bf2f(lg.x >> 16));
;     float y2 = (bf2f(hl.y & 0xffff) + bf2f(pp.y & 0xffff) * hs.z) * gelu_tanh(bf2f(lg.y & 0xffff));
;     float y3 = (bf2f(hl.y >> 16) + bf2f(pp.y >> 16) * hs.w) * gelu_tanh(bf2f(lg.y >> 16));
;     *(uint2*)(OL + o) = uint2{pack2(y0, y1), pack2(y2, y3)};
;   }
; }
.LBB0_1908:
	v_mov_b32_e32 v1, v185
	v_add_u32_e32 v2, s30, v2
	v_ashrrev_i32_e32 v0, 7, v1
	v_add_u32_e32 v0, v4, v0
	v_add_u32_e32 v6, 0xffff8000, v0
	v_lshlrev_b32_e32 v1, 2, v1
	v_lshrrev_b32_e32 v6, 5, v6
	s_waitcnt lgkmcnt(0)
	v_and_b32_e32 v5, 0x1fc, v1
	v_cmp_gt_i32_e32 vcc, s20, v0
	v_ashrrev_i32_e32 v1, 6, v0
	v_add_u32_e32 v6, 0x200, v6
	v_cndmask_b32_e32 v6, v6, v1, vcc
	v_ashrrev_i32_e32 v1, 31, v0
	v_lshlrev_b64 v[0:1], 10, v[0:1]
	v_lshl_or_b32 v0, v5, 1, v0
	v_lshl_add_u64 v[8:9], s[12:13], 0, v[0:1]
	global_load_dwordx2 v[64:65], v[8:9], off
	v_lshl_add_u64 v[8:9], s[24:25], 0, v[0:1]
	global_load_dwordx2 v[66:67], v[8:9], off
	v_lshl_add_u64 v[8:9], s[10:11], 0, v[0:1]
	global_load_dwordx2 v[68:69], v[8:9], off
	v_ashrrev_i32_e32 v7, 31, v6
	v_lshlrev_b64 v[6:7], 11, v[6:7]
	v_lshl_add_u64 v[6:7], s[26:27], 0, v[6:7]
	v_lshlrev_b32_e32 v172, 2, v5
	v_lshl_add_u64 v[6:7], v[6:7], 0, v[172:173]
	global_load_dwordx4 v[104:107], v[6:7], off
	v_lshl_add_u64 v[96:97], s[28:29], 0, v[0:1]
	s_movk_i32 s8, 0x103f
	v_mov_b32_e32 v1, v185
	s_nop 0
	v_add_u32_e32 v0, 0x100, v1
	v_ashrrev_i32_e32 v0, 7, v0
	v_add_u32_e32 v0, v4, v0
	v_add_u32_e32 v6, 0xffff8000, v0
	v_lshlrev_b32_e32 v1, 2, v1
	v_lshrrev_b32_e32 v6, 5, v6
	v_and_b32_e32 v5, 0x1fc, v1
	v_cmp_gt_i32_e32 vcc, s20, v0
	v_ashrrev_i32_e32 v1, 6, v0
	v_add_u32_e32 v6, 0x200, v6
	v_cndmask_b32_e32 v6, v6, v1, vcc
	v_ashrrev_i32_e32 v1, 31, v0
	v_lshlrev_b64 v[0:1], 10, v[0:1]
	v_lshl_or_b32 v0, v5, 1, v0
	v_lshl_add_u64 v[8:9], s[12:13], 0, v[0:1]
	global_load_dwordx2 v[72:73], v[8:9], off
	v_lshl_add_u64 v[8:9], s[24:25], 0, v[0:1]
	global_load_dwordx2 v[74:75], v[8:9], off
	v_lshl_add_u64 v[8:9], s[10:11], 0, v[0:1]
	global_load_dwordx2 v[76:77], v[8:9], off
	v_ashrrev_i32_e32 v7, 31, v6
	v_lshlrev_b64 v[6:7], 11, v[6:7]
	v_lshl_add_u64 v[6:7], s[26:27], 0, v[6:7]
	v_lshlrev_b32_e32 v172, 2, v5
	v_lshl_add_u64 v[6:7], v[6:7], 0, v[172:173]
	global_load_dwordx4 v[108:111], v[6:7], off
	v_lshl_add_u64 v[98:99], s[28:29], 0, v[0:1]
	v_mov_b32_e32 v1, v185
	s_nop 0
	v_add_u32_e32 v0, 0x200, v1
	v_ashrrev_i32_e32 v0, 7, v0
	v_add_u32_e32 v0, v4, v0
	v_add_u32_e32 v6, 0xffff8000, v0
	v_lshlrev_b32_e32 v1, 2, v1
	v_lshrrev_b32_e32 v6, 5, v6
	v_and_b32_e32 v5, 0x1fc, v1
	v_cmp_gt_i32_e32 vcc, s20, v0
	v_ashrrev_i32_e32 v1, 6, v0
	v_add_u32_e32 v6, 0x200, v6
	v_cndmask_b32_e32 v6, v6, v1, vcc
	v_ashrrev_i32_e32 v1, 31, v0
	v_lshlrev_b64 v[0:1], 10, v[0:1]
	v_lshl_or_b32 v0, v5, 1, v0
	v_lshl_add_u64 v[8:9], s[12:13], 0, v[0:1]
	global_load_dwordx2 v[80:81], v[8:9], off
	v_lshl_add_u64 v[8:9], s[24:25], 0, v[0:1]
	global_load_dwordx2 v[82:83], v[8:9], off
	v_lshl_add_u64 v[8:9], s[10:11], 0, v[0:1]
	global_load_dwordx2 v[84:85], v[8:9], off
	v_ashrrev_i32_e32 v7, 31, v6
	v_lshlrev_b64 v[6:7], 11, v[6:7]
	v_lshl_add_u64 v[6:7], s[26:27], 0, v[6:7]
	v_lshlrev_b32_e32 v172, 2, v5
	v_lshl_add_u64 v[6:7], v[6:7], 0, v[172:173]
	global_load_dwordx4 v[112:115], v[6:7], off
	v_lshl_add_u64 v[100:101], s[28:29], 0, v[0:1]
	v_mov_b32_e32 v0, v185
	s_nop 0
	v_add_u32_e32 v1, 0x300, v0
	v_ashrrev_i32_e32 v1, 7, v1
	v_add_u32_e32 v6, v4, v1
	v_add_u32_e32 v1, 0xffff8000, v6
	v_lshlrev_b32_e32 v0, 2, v0
	v_lshrrev_b32_e32 v1, 5, v1
	v_and_b32_e32 v5, 0x1fc, v0
	v_cmp_gt_i32_e32 vcc, s20, v6
	v_ashrrev_i32_e32 v0, 6, v6
	v_add_u32_e32 v1, 0x200, v1
	v_ashrrev_i32_e32 v7, 31, v6
	v_cndmask_b32_e32 v8, v1, v0, vcc
	v_lshlrev_b64 v[0:1], 10, v[6:7]
	v_lshl_or_b32 v0, v5, 1, v0
	v_lshl_add_u64 v[6:7], s[12:13], 0, v[0:1]
	global_load_dwordx2 v[88:89], v[6:7], off
	v_lshl_add_u64 v[6:7], s[24:25], 0, v[0:1]
	global_load_dwordx2 v[90:91], v[6:7], off
	v_lshl_add_u64 v[6:7], s[10:11], 0, v[0:1]
	global_load_dwordx2 v[92:93], v[6:7], off
	v_ashrrev_i32_e32 v9, 31, v8
	v_lshlrev_b64 v[6:7], 11, v[8:9]
	v_lshl_add_u64 v[6:7], s[26:27], 0, v[6:7]
	v_lshlrev_b32_e32 v172, 2, v5
	v_lshl_add_u64 v[6:7], v[6:7], 0, v[172:173]
	global_load_dwordx4 v[116:119], v[6:7], off
	v_cmp_lt_i32_e32 vcc, s8, v2
	v_lshl_add_u64 v[102:103], s[28:29], 0, v[0:1]
	v_add_u32_e32 v4, s9, v4
	s_or_b64 s[6:7], vcc, s[6:7]
	s_waitcnt vmcnt(15)
	v_lshlrev_b32_e32 v16, 16, v64
	v_and_b32_e32 v17, 0xffff0000, v64
	s_waitcnt vmcnt(14)
	v_lshlrev_b32_e32 v18, 16, v66
	v_and_b32_e32 v19, 0xffff0000, v66
	s_waitcnt vmcnt(13)
	v_lshlrev_b32_e32 v20, 16, v68
	v_mul_f32_e32 v5, 0x3d372713, v20
	v_mul_f32_e32 v5, v5, v20
	v_mov_b32_e32 v10, v20
	v_fmac_f32_e32 v10, v5, v10
	v_mul_f32_e32 v5, 0x3f4c422a, v10
	v_add_f32_e32 v5, v5, v5
	v_mul_f32_e32 v5, 0xbfb8aa3b, v5
	v_exp_f32_e32 v5, v5
	v_and_b32_e32 v21, 0xffff0000, v68
	v_mov_b32_e32 v10, v21
	v_lshlrev_b32_e32 v14, 16, v69
	v_add_f32_e32 v5, 1.0, v5
	v_rcp_f32_e32 v22, v5
	v_mul_f32_e32 v5, 0x3d372713, v21
	v_mul_f32_e32 v5, v5, v21
	v_fmac_f32_e32 v10, v5, v10
	v_mul_f32_e32 v5, 0x3f4c422a, v10
	v_add_f32_e32 v5, v5, v5
	v_mul_f32_e32 v5, 0xbfb8aa3b, v5
	v_exp_f32_e32 v5, v5
	s_waitcnt vmcnt(12)
	v_pk_fma_f32 v[6:7], v[104:105], v[18:19], v[16:17]
	v_and_b32_e32 v15, 0xffff0000, v69
	v_lshlrev_b32_e32 v10, 16, v65
	v_add_f32_e32 v5, 1.0, v5
	v_rcp_f32_e32 v23, v5
	v_mul_f32_e32 v5, 0x3d372713, v14
	v_mul_f32_e32 v5, v5, v14
	v_lshlrev_b32_e32 v12, 16, v67
	v_pk_mul_f32 v[16:17], v[22:23], v[20:21]
	v_and_b32_e32 v11, 0xffff0000, v65
	v_pk_mul_f32 v[6:7], v[6:7], v[16:17]
	v_mov_b32_e32 v16, v14
	v_fmac_f32_e32 v16, v5, v16
	v_mul_f32_e32 v5, 0x3f4c422a, v16
	v_add_f32_e32 v5, v5, v5
	v_mul_f32_e32 v5, 0xbfb8aa3b, v5
	v_exp_f32_e32 v5, v5
	v_and_b32_e32 v13, 0xffff0000, v67
	v_pk_fma_f32 v[8:9], v[106:107], v[12:13], v[10:11]
	v_mov_b32_e32 v10, v15
	v_add_f32_e32 v5, 1.0, v5
	v_rcp_f32_e32 v16, v5
	v_mul_f32_e32 v5, 0x3d372713, v15
	v_mul_f32_e32 v5, v5, v15
	v_fmac_f32_e32 v10, v5, v10
	v_mul_f32_e32 v5, 0x3f4c422a, v10
	v_add_f32_e32 v5, v5, v5
	v_mul_f32_e32 v5, 0xbfb8aa3b, v5
	v_exp_f32_e32 v5, v5
	v_cvt_pk_bf16_f32 v6, v6, v7
	v_add_f32_e32 v5, 1.0, v5
	v_rcp_f32_e32 v17, v5
	s_nop 0
	v_pk_mul_f32 v[10:11], v[16:17], v[14:15]
	s_nop 0
	v_pk_mul_f32 v[8:9], v[8:9], v[10:11]
	s_nop 0
	v_cvt_pk_bf16_f32 v7, v8, v9
	global_store_dwordx2 v[96:97], v[6:7], off
	s_waitcnt vmcnt(12)
; DI int TID() { int t = threadIdx.x & 255; asm volatile("" : "+v"(t)); return t; }
; DI float bf2f(u16 h) { return __uint_as_float(((unsigned)h) << 16); }
; DI unsigned pack2(float a, float b) { f32v2_t v = {a, b}; bf16v2_t r = __builtin_convertvector(v, bf16v2_t); return __builtin_bit_cast(unsigned, r); }
; DI float gelu_tanh(float x) { float u = 0.7978845608028654f * (x + 0.044715f * x * x * x); return x * sigmoidf_(2.f * u); }
; #define HS() (smem + (TID512() >> 8) * HALF_LDS)
; DI void lru3_item(const Params& p, int it) {
;   const u16* HL = (const u16*)(p.ws + O_HL);
;   const u16* PPp = (const u16*)(p.ws + O_PP);
;   const u16* LG = (const u16*)(p.ws + O_LG);
;   const float* HS = (const float*)(p.ws + O_HS);
;   u16* OL = (u16*)(p.ws + O_OL);
; #pragma unroll
;   for (int i = 0; i < 4; ++i) {
;     const int id = TID() + i * 256;
;     const int row = it * 8 + (id >> 7), c4 = (id & 127) * 4;
;     const int ci = row < MP ? (row >> 6) : MP / 64 + ((row - MP) >> 5);
;     const size_t o = (size_t)row * 512 + c4;
;     const uint2 hl = *(const uint2*)(HL + o), pp = *(const uint2*)(PPp + o), lg = *(const uint2*)(LG + o);
;     const float4 hs = *(const float4*)(HS + (size_t)ci * 512 + c4);
;     float y0 = (bf2f(hl.x & 0xffff) + bf2f(pp.x & 0xffff) * hs.x) * gelu_tanh(bf2f(lg.x & 0xffff));
;     float y1 = (bf2f(hl.x >> 16) + bf2f(pp.x >> 16) * hs.y) * gelu_tanh(bf2f(lg.x >> 16));
;     float y2 = (bf2f(hl.y & 0xffff) + bf2f(pp.y & 0xffff) * hs.z) * gelu_tanh(bf2f(lg.y & 0xffff));
;     float y3 = (bf2f(hl.y >> 16) + bf2f(pp.y >> 16) * hs.w) * gelu_tanh(bf2f(lg.y >> 16));
;     *(uint2*)(OL + o) = uint2{pack2(y0, y1), pack2(y2, y3)};
;   }
; }
	v_lshlrev_b32_e32 v16, 16, v72
	v_and_b32_e32 v17, 0xffff0000, v72
	s_waitcnt vmcnt(11)
	v_lshlrev_b32_e32 v18, 16, v74
	v_and_b32_e32 v19, 0xffff0000, v74
	s_waitcnt vmcnt(10)
	v_lshlrev_b32_e32 v20, 16, v76
	v_mul_f32_e32 v5, 0x3d372713, v20
	v_mul_f32_e32 v5, v5, v20
	v_mov_b32_e32 v10, v20
	v_fmac_f32_e32 v10, v5, v10
	v_mul_f32_e32 v5, 0x3f4c422a, v10
	v_add_f32_e32 v5, v5, v5
	v_mul_f32_e32 v5, 0xbfb8aa3b, v5
	v_exp_f32_e32 v5, v5
	v_and_b32_e32 v21, 0xffff0000, v76
	v_mov_b32_e32 v10, v21
	v_lshlrev_b32_e32 v14, 16, v77
	v_add_f32_e32 v5, 1.0, v5
	v_rcp_f32_e32 v22, v5
	v_mul_f32_e32 v5, 0x3d372713, v21
	v_mul_f32_e32 v5, v5, v21
	v_fmac_f32_e32 v10, v5, v10
	v_mul_f32_e32 v5, 0x3f4c422a, v10
	v_add_f32_e32 v5, v5, v5
	v_mul_f32_e32 v5, 0xbfb8aa3b, v5
	v_exp_f32_e32 v5, v5
	s_waitcnt vmcnt(9)
	v_pk_fma_f32 v[6:7], v[108:109], v[18:19], v[16:17]
	v_and_b32_e32 v15, 0xffff0000, v77
	v_lshlrev_b32_e32 v10, 16, v73
	v_add_f32_e32 v5, 1.0, v5
	v_rcp_f32_e32 v23, v5
	v_mul_f32_e32 v5, 0x3d372713, v14
	v_mul_f32_e32 v5, v5, v14
	v_lshlrev_b32_e32 v12, 16, v75
	v_pk_mul_f32 v[16:17], v[22:23], v[20:21]
	v_and_b32_e32 v11, 0xffff0000, v73
	v_pk_mul_f32 v[6:7], v[6:7], v[16:17]
	v_mov_b32_e32 v16, v14
	v_fmac_f32_e32 v16, v5, v16
	v_mul_f32_e32 v5, 0x3f4c422a, v16
	v_add_f32_e32 v5, v5, v5
	v_mul_f32_e32 v5, 0xbfb8aa3b, v5
	v_exp_f32_e32 v5, v5
	v_and_b32_e32 v13, 0xffff0000, v75
	v_pk_fma_f32 v[8:9], v[110:111], v[12:13], v[10:11]
	v_mov_b32_e32 v10, v15
	v_add_f32_e32 v5, 1.0, v5
	v_rcp_f32_e32 v16, v5
	v_mul_f32_e32 v5, 0x3d372713, v15
	v_mul_f32_e32 v5, v5, v15
	v_fmac_f32_e32 v10, v5, v10
	v_mul_f32_e32 v5, 0x3f4c422a, v10
	v_add_f32_e32 v5, v5, v5
	v_mul_f32_e32 v5, 0xbfb8aa3b, v5
	v_exp_f32_e32 v5, v5
	v_cvt_pk_bf16_f32 v6, v6, v7
	v_add_f32_e32 v5, 1.0, v5
	v_rcp_f32_e32 v17, v5
	s_nop 0
	v_pk_mul_f32 v[10:11], v[16:17], v[14:15]
	s_nop 0
	v_pk_mul_f32 v[8:9], v[8:9], v[10:11]
	s_nop 0
	v_cvt_pk_bf16_f32 v7, v8, v9
	global_store_dwordx2 v[98:99], v[6:7], off
	s_waitcnt vmcnt(9)
	v_lshlrev_b32_e32 v16, 16, v80
	v_and_b32_e32 v17, 0xffff0000, v80
	s_waitcnt vmcnt(8)
	v_lshlrev_b32_e32 v18, 16, v82
	v_and_b32_e32 v19, 0xffff0000, v82
	s_waitcnt vmcnt(7)
	v_lshlrev_b32_e32 v20, 16, v84
	v_mul_f32_e32 v5, 0x3d372713, v20
	v_mul_f32_e32 v5, v5, v20
	v_mov_b32_e32 v10, v20
	v_fmac_f32_e32 v10, v5, v10
	v_mul_f32_e32 v5, 0x3f4c422a, v10
	v_add_f32_e32 v5, v5, v5
	v_mul_f32_e32 v5, 0xbfb8aa3b, v5
	v_exp_f32_e32 v5, v5
	v_and_b32_e32 v21, 0xffff0000, v84
	v_mov_b32_e32 v10, v21
	v_lshlrev_b32_e32 v14, 16, v85
	v_add_f32_e32 v5, 1.0, v5
	v_rcp_f32_e32 v22, v5
	v_mul_f32_e32 v5, 0x3d372713, v21
	v_mul_f32_e32 v5, v5, v21
	v_fmac_f32_e32 v10, v5, v10
	v_mul_f32_e32 v5, 0x3f4c422a, v10
	v_add_f32_e32 v5, v5, v5
	v_mul_f32_e32 v5, 0xbfb8aa3b, v5
	v_exp_f32_e32 v5, v5
	s_waitcnt vmcnt(6)
	v_pk_fma_f32 v[6:7], v[112:113], v[18:19], v[16:17]
	v_and_b32_e32 v15, 0xffff0000, v85
	v_lshlrev_b32_e32 v10, 16, v81
	v_add_f32_e32 v5, 1.0, v5
	v_rcp_f32_e32 v23, v5
	v_mul_f32_e32 v5, 0x3d372713, v14
	v_mul_f32_e32 v5, v5, v14
	v_lshlrev_b32_e32 v12, 16, v83
	v_pk_mul_f32 v[16:17], v[22:23], v[20:21]
	v_and_b32_e32 v11, 0xffff0000, v81
	v_pk_mul_f32 v[6:7], v[6:7], v[16:17]
	v_mov_b32_e32 v16, v14
	v_fmac_f32_e32 v16, v5, v16
	v_mul_f32_e32 v5, 0x3f4c422a, v16
	v_add_f32_e32 v5, v5, v5
	v_mul_f32_e32 v5, 0xbfb8aa3b, v5
	v_exp_f32_e32 v5, v5
	v_and_b32_e32 v13, 0xffff0000, v83
	v_pk_fma_f32 v[8:9], v[114:115], v[12:13], v[10:11]
	v_mov_b32_e32 v10, v15
	v_add_f32_e32 v5, 1.0, v5
	v_rcp_f32_e32 v16, v5
	v_mul_f32_e32 v5, 0x3d372713, v15
	v_mul_f32_e32 v5, v5, v15
	v_fmac_f32_e32 v10, v5, v10
	v_mul_f32_e32 v5, 0x3f4c422a, v10
	v_add_f32_e32 v5, v5, v5
	v_mul_f32_e32 v5, 0xbfb8aa3b, v5
	v_exp_f32_e32 v5, v5
	v_cvt_pk_bf16_f32 v6, v6, v7
	v_add_f32_e32 v5, 1.0, v5
	v_rcp_f32_e32 v17, v5
	s_nop 0
	v_pk_mul_f32 v[10:11], v[16:17], v[14:15]
	s_nop 0
	v_pk_mul_f32 v[8:9], v[8:9], v[10:11]
	s_nop 0
	v_cvt_pk_bf16_f32 v7, v8, v9
	global_store_dwordx2 v[100:101], v[6:7], off
	s_waitcnt vmcnt(6)
	v_lshlrev_b32_e32 v16, 16, v88
	v_and_b32_e32 v17, 0xffff0000, v88
	s_waitcnt vmcnt(5)
	v_lshlrev_b32_e32 v18, 16, v90
	v_and_b32_e32 v19, 0xffff0000, v90
	s_waitcnt vmcnt(4)
	v_lshlrev_b32_e32 v20, 16, v92
	v_mul_f32_e32 v5, 0x3d372713, v20
	v_mul_f32_e32 v5, v5, v20
	v_mov_b32_e32 v10, v20
	v_fmac_f32_e32 v10, v5, v10
	v_mul_f32_e32 v5, 0x3f4c422a, v10
	v_add_f32_e32 v5, v5, v5
	v_mul_f32_e32 v5, 0xbfb8aa3b, v5
	v_exp_f32_e32 v5, v5
	v_and_b32_e32 v21, 0xffff0000, v92
	v_mov_b32_e32 v10, v21
	v_lshlrev_b32_e32 v14, 16, v93
	v_add_f32_e32 v5, 1.0, v5
	v_rcp_f32_e32 v22, v5
	v_mul_f32_e32 v5, 0x3d372713, v21
	v_mul_f32_e32 v5, v5, v21
	v_fmac_f32_e32 v10, v5, v10
	v_mul_f32_e32 v5, 0x3f4c422a, v10
	v_add_f32_e32 v5, v5, v5
	v_mul_f32_e32 v5, 0xbfb8aa3b, v5
	v_exp_f32_e32 v5, v5
	s_waitcnt vmcnt(3)
	v_pk_fma_f32 v[6:7], v[116:117], v[18:19], v[16:17]
	v_and_b32_e32 v15, 0xffff0000, v93
	v_lshlrev_b32_e32 v10, 16, v89
	v_add_f32_e32 v5, 1.0, v5
	v_rcp_f32_e32 v23, v5
	v_mul_f32_e32 v5, 0x3d372713, v14
	v_mul_f32_e32 v5, v5, v14
	v_lshlrev_b32_e32 v12, 16, v91
	v_pk_mul_f32 v[16:17], v[22:23], v[20:21]
	v_and_b32_e32 v11, 0xffff0000, v89
	v_pk_mul_f32 v[6:7], v[6:7], v[16:17]
	v_mov_b32_e32 v16, v14
	v_fmac_f32_e32 v16, v5, v16
	v_mul_f32_e32 v5, 0x3f4c422a, v16
	v_add_f32_e32 v5, v5, v5
	v_mul_f32_e32 v5, 0xbfb8aa3b, v5
	v_exp_f32_e32 v5, v5
	v_and_b32_e32 v13, 0xffff0000, v91
	v_pk_fma_f32 v[8:9], v[118:119], v[12:13], v[10:11]
	v_mov_b32_e32 v10, v15
	v_add_f32_e32 v5, 1.0, v5
	v_rcp_f32_e32 v16, v5
	v_mul_f32_e32 v5, 0x3d372713, v15
	v_mul_f32_e32 v5, v5, v15
	v_fmac_f32_e32 v10, v5, v10
	v_mul_f32_e32 v5, 0x3f4c422a, v10
	v_add_f32_e32 v5, v5, v5
	v_mul_f32_e32 v5, 0xbfb8aa3b, v5
	v_exp_f32_e32 v5, v5
	v_cvt_pk_bf16_f32 v6, v6, v7
	v_add_f32_e32 v5, 1.0, v5
	v_rcp_f32_e32 v17, v5
	s_nop 0
	v_pk_mul_f32 v[10:11], v[16:17], v[14:15]
	s_nop 0
	v_pk_mul_f32 v[8:9], v[8:9], v[10:11]
	s_nop 0
	v_cvt_pk_bf16_f32 v7, v8, v9
	global_store_dwordx2 v[102:103], v[6:7], off
	s_andn2_b64 exec, exec, s[6:7]
	s_cbranch_execnz .LBB0_1908
